# PRO adaLN GEMV: weight loads prefetched one loop iteration ahead
# speedup vs baseline: 1.0133x; 1.0105x over previous
.LBB0_1021:
	s_mul_hi_i32 s0, s8, 0x2aaaaaab
	s_lshr_b32 s1, s0, 31
	s_ashr_i32 s0, s0, 5
	s_add_i32 s24, s0, s1
	s_mul_i32 s0, s24, 0xc0
	s_sub_i32 s0, s8, s0
	s_lshl_b32 s0, s0, 5
	s_ashr_i32 s1, s0, 31
	s_mul_i32 s26, s24, 0x1800000
	s_lshl_b64 s[22:23], s[0:1], 2
	s_mul_hi_i32 s25, s24, 0x1800000
	s_add_u32 s22, s26, s22
	s_addc_u32 s23, s25, s23
	v_mov_b32_e32 v22, 0
	v_lshl_add_u64 v[20:21], v[18:19], 0, s[22:23]
	s_mov_b32 s22, -4
	v_mov_b32_e32 v38, v35
	v_mov_b32_e32 v23, v22
	v_mov_b32_e32 v24, v22
	v_mov_b32_e32 v25, v22
	v_mov_b32_e32 v26, v22
	v_mov_b32_e32 v27, v22
	v_mov_b32_e32 v28, v22
	v_mov_b32_e32 v29, v22
	v_mov_b32_e32 v0, v22
	v_add_co_u32_e32 v116, vcc, 0xfff4c000, v20
	s_nop 1
	v_addc_co_u32_e32 v117, vcc, -1, v21, vcc
	global_load_dword v100, v[116:117], off
	v_add_co_u32_e32 v116, vcc, 0xfff58000, v20
	s_nop 1
	v_addc_co_u32_e32 v117, vcc, -1, v21, vcc
	global_load_dword v101, v[116:117], off
	v_add_co_u32_e32 v116, vcc, 0xfff64000, v20
	s_nop 1
	v_addc_co_u32_e32 v117, vcc, -1, v21, vcc
	global_load_dword v102, v[116:117], off
	v_add_co_u32_e32 v116, vcc, 0xfff70000, v20
	s_nop 1
	v_addc_co_u32_e32 v117, vcc, -1, v21, vcc
	global_load_dword v103, v[116:117], off
	v_add_co_u32_e32 v116, vcc, 0xfff7c000, v20
	s_nop 1
	v_addc_co_u32_e32 v117, vcc, -1, v21, vcc
	global_load_dword v104, v[116:117], off
	v_add_co_u32_e32 v116, vcc, 0xfff88000, v20
	s_nop 1
	v_addc_co_u32_e32 v117, vcc, -1, v21, vcc
	global_load_dword v105, v[116:117], off
	v_add_co_u32_e32 v116, vcc, 0xfff94000, v20
	s_nop 1
	v_addc_co_u32_e32 v117, vcc, -1, v21, vcc
	global_load_dword v106, v[116:117], off
	v_add_co_u32_e32 v116, vcc, 0xfffa0000, v20
	s_nop 1
	v_addc_co_u32_e32 v117, vcc, -1, v21, vcc
	global_load_dword v107, v[116:117], off
	v_add_co_u32_e32 v116, vcc, 0xfffac000, v20
	s_nop 1
	v_addc_co_u32_e32 v117, vcc, -1, v21, vcc
	global_load_dword v108, v[116:117], off
	v_add_co_u32_e32 v116, vcc, 0xfffb8000, v20
	s_nop 1
	v_addc_co_u32_e32 v117, vcc, -1, v21, vcc
	global_load_dword v109, v[116:117], off
	v_add_co_u32_e32 v116, vcc, 0xfffc4000, v20
	s_nop 1
	v_addc_co_u32_e32 v117, vcc, -1, v21, vcc
	global_load_dword v110, v[116:117], off
	v_add_co_u32_e32 v116, vcc, 0xfffd0000, v20
	s_nop 1
	v_addc_co_u32_e32 v117, vcc, -1, v21, vcc
	global_load_dword v111, v[116:117], off
	v_add_co_u32_e32 v116, vcc, 0xfffdc000, v20
	s_nop 1
	v_addc_co_u32_e32 v117, vcc, -1, v21, vcc
	global_load_dword v112, v[116:117], off
	v_add_co_u32_e32 v116, vcc, 0xfffe8000, v20
	s_nop 1
	v_addc_co_u32_e32 v117, vcc, -1, v21, vcc
	global_load_dword v113, v[116:117], off
	v_add_co_u32_e32 v116, vcc, 0xffff4000, v20
	s_nop 1
	v_addc_co_u32_e32 v117, vcc, -1, v21, vcc
	global_load_dword v114, v[116:117], off
	global_load_dword v115, v[20:21], off
.LBB0_1022:
	s_waitcnt vmcnt(0)
	v_mov_b32_e32 v120, v100
	v_mov_b32_e32 v121, v101
	v_mov_b32_e32 v122, v102
	v_mov_b32_e32 v123, v103
	v_mov_b32_e32 v124, v104
	v_mov_b32_e32 v125, v105
	v_mov_b32_e32 v126, v106
	v_mov_b32_e32 v127, v107
	v_mov_b32_e32 v128, v108
	v_mov_b32_e32 v129, v109
	v_mov_b32_e32 v130, v110
	v_mov_b32_e32 v131, v111
	v_mov_b32_e32 v132, v112
	v_mov_b32_e32 v133, v113
	v_mov_b32_e32 v134, v114
	v_mov_b32_e32 v135, v115
	s_cmp_lg_u32 s22, 44
	s_cbranch_scc0 .Lmods_nopf
	v_add_co_u32_e32 v116, vcc, 0xc000, v20
	s_nop 1
	v_addc_co_u32_e32 v117, vcc, 0, v21, vcc
	global_load_dword v100, v[116:117], off
	v_add_co_u32_e32 v116, vcc, 0x18000, v20
	s_nop 1
	v_addc_co_u32_e32 v117, vcc, 0, v21, vcc
	global_load_dword v101, v[116:117], off
	v_add_co_u32_e32 v116, vcc, 0x24000, v20
	s_nop 1
	v_addc_co_u32_e32 v117, vcc, 0, v21, vcc
	global_load_dword v102, v[116:117], off
	v_add_co_u32_e32 v116, vcc, 0x30000, v20
	s_nop 1
	v_addc_co_u32_e32 v117, vcc, 0, v21, vcc
	global_load_dword v103, v[116:117], off
	v_add_co_u32_e32 v116, vcc, 0x3c000, v20
	s_nop 1
	v_addc_co_u32_e32 v117, vcc, 0, v21, vcc
	global_load_dword v104, v[116:117], off
	v_add_co_u32_e32 v116, vcc, 0x48000, v20
	s_nop 1
	v_addc_co_u32_e32 v117, vcc, 0, v21, vcc
	global_load_dword v105, v[116:117], off
	v_add_co_u32_e32 v116, vcc, 0x54000, v20
	s_nop 1
	v_addc_co_u32_e32 v117, vcc, 0, v21, vcc
	global_load_dword v106, v[116:117], off
	v_add_co_u32_e32 v116, vcc, 0x60000, v20
	s_nop 1
	v_addc_co_u32_e32 v117, vcc, 0, v21, vcc
	global_load_dword v107, v[116:117], off
	v_add_co_u32_e32 v116, vcc, 0x6c000, v20
	s_nop 1
	v_addc_co_u32_e32 v117, vcc, 0, v21, vcc
	global_load_dword v108, v[116:117], off
	v_add_co_u32_e32 v116, vcc, 0x78000, v20
	s_nop 1
	v_addc_co_u32_e32 v117, vcc, 0, v21, vcc
	global_load_dword v109, v[116:117], off
	v_add_co_u32_e32 v116, vcc, 0x84000, v20
	s_nop 1
	v_addc_co_u32_e32 v117, vcc, 0, v21, vcc
	global_load_dword v110, v[116:117], off
	v_add_co_u32_e32 v116, vcc, 0x90000, v20
	s_nop 1
	v_addc_co_u32_e32 v117, vcc, 0, v21, vcc
	global_load_dword v111, v[116:117], off
	v_add_co_u32_e32 v116, vcc, 0x9c000, v20
	s_nop 1
	v_addc_co_u32_e32 v117, vcc, 0, v21, vcc
	global_load_dword v112, v[116:117], off
	v_add_co_u32_e32 v116, vcc, 0xa8000, v20
	s_nop 1
	v_addc_co_u32_e32 v117, vcc, 0, v21, vcc
	global_load_dword v113, v[116:117], off
	v_add_co_u32_e32 v116, vcc, 0xb4000, v20
	s_nop 1
	v_addc_co_u32_e32 v117, vcc, 0, v21, vcc
	global_load_dword v114, v[116:117], off
	v_add_co_u32_e32 v116, vcc, 0xc0000, v20
	s_nop 1
	v_addc_co_u32_e32 v117, vcc, 0, v21, vcc
	global_load_dword v115, v[116:117], off
.Lmods_nopf:
	v_add_co_u32_e32 v2, vcc, 0xfff4c000, v20
	s_mov_b32 s23, 0xfff7c000
	s_nop 0
	v_addc_co_u32_e32 v3, vcc, -1, v21, vcc
	v_mov_b32_e32 v48, v120
	v_add_co_u32_e32 v2, vcc, 0xfff58000, v20
	s_add_i32 s22, s22, 16
	s_nop 0
	v_addc_co_u32_e32 v3, vcc, -1, v21, vcc
	v_mov_b32_e32 v50, v121
	v_add_co_u32_e32 v2, vcc, 0xfff64000, v20
	s_mov_b64 s[26:27], 0xc0000
	s_nop 0
	v_addc_co_u32_e32 v3, vcc, -1, v21, vcc
	v_mov_b32_e32 v34, v122
	v_add_co_u32_e32 v2, vcc, 0xfff70000, v20
	s_cmp_gt_u32 s22, 59
	s_nop 0
	v_addc_co_u32_e32 v3, vcc, -1, v21, vcc
	v_mov_b32_e32 v52, v123
	ds_read_b128 v[30:33], v38
	ds_read_b128 v[10:13], v38 offset:16
	ds_read_b128 v[6:9], v38 offset:32
	ds_read_b128 v[2:5], v38 offset:48
	ds_read_b128 v[40:43], v38 offset:2048
	s_waitcnt lgkmcnt(4)
	v_mov_b32_e32 v44, v30
	s_waitcnt lgkmcnt(0)
	v_mov_b32_e32 v45, v40
	v_mov_b32_e32 v40, v31
	v_pk_mul_f32 v[30:31], v[50:51], v[40:41] op_sel_hi:[0,1]
	v_mov_b32_e32 v41, v42
	v_mov_b32_e32 v42, v33
	v_mov_b32_e32 v40, v32
	v_pk_fma_f32 v[30:31], v[48:49], v[44:45], v[30:31] op_sel_hi:[0,1,1]
	v_pk_mul_f32 v[32:33], v[52:53], v[42:43] op_sel_hi:[0,1]
	v_pk_fma_f32 v[32:33], v[34:35], v[40:41], v[32:33] op_sel_hi:[0,1,1]
	ds_read_b128 v[40:43], v38 offset:4096
	ds_read_b128 v[44:47], v38 offset:6144
	v_pk_add_f32 v[30:31], v[30:31], v[32:33]
	s_nop 0
	v_pk_add_f32 v[32:33], v[22:23], v[30:31]
	s_waitcnt lgkmcnt(1)
	v_mov_b32_e32 v22, v40
	s_waitcnt lgkmcnt(0)
	v_mov_b32_e32 v23, v44
	v_mov_b32_e32 v44, v41
	v_pk_mul_f32 v[30:31], v[50:51], v[44:45] op_sel_hi:[0,1]
	v_pk_fma_f32 v[22:23], v[48:49], v[22:23], v[30:31] op_sel_hi:[0,1,1]
	v_mov_b32_e32 v31, v46
	v_mov_b32_e32 v46, v43
	v_mov_b32_e32 v30, v42
	v_pk_mul_f32 v[40:41], v[52:53], v[46:47] op_sel_hi:[0,1]
	v_pk_fma_f32 v[30:31], v[34:35], v[30:31], v[40:41] op_sel_hi:[0,1,1]
	v_pk_add_f32 v[22:23], v[22:23], v[30:31]
	s_nop 0
	v_pk_add_f32 v[30:31], v[24:25], v[22:23]
	ds_read_b128 v[22:25], v38 offset:8192
	ds_read_b128 v[40:43], v38 offset:10240
	s_waitcnt lgkmcnt(1)
	v_mov_b32_e32 v44, v22
	s_waitcnt lgkmcnt(0)
	v_mov_b32_e32 v45, v40
	v_mov_b32_e32 v40, v23
	v_pk_mul_f32 v[22:23], v[50:51], v[40:41] op_sel_hi:[0,1]
	v_mov_b32_e32 v41, v42
	v_mov_b32_e32 v42, v25
	v_mov_b32_e32 v40, v24
	v_pk_mul_f32 v[24:25], v[52:53], v[42:43] op_sel_hi:[0,1]
	v_pk_fma_f32 v[22:23], v[48:49], v[44:45], v[22:23] op_sel_hi:[0,1,1]
	v_pk_fma_f32 v[24:25], v[34:35], v[40:41], v[24:25] op_sel_hi:[0,1,1]
	v_pk_add_f32 v[22:23], v[22:23], v[24:25]
	s_nop 0
	v_pk_add_f32 v[26:27], v[26:27], v[22:23]
	ds_read_b128 v[22:25], v38 offset:12288
	ds_read_b128 v[40:43], v38 offset:14336
	s_waitcnt lgkmcnt(1)
	v_mov_b32_e32 v44, v22
	s_waitcnt lgkmcnt(0)
	v_mov_b32_e32 v45, v40
	v_mov_b32_e32 v40, v23
	v_pk_mul_f32 v[22:23], v[50:51], v[40:41] op_sel_hi:[0,1]
	v_mov_b32_e32 v41, v42
	v_mov_b32_e32 v42, v25
	v_mov_b32_e32 v40, v24
	v_pk_mul_f32 v[24:25], v[52:53], v[42:43] op_sel_hi:[0,1]
	v_pk_fma_f32 v[24:25], v[34:35], v[40:41], v[24:25] op_sel_hi:[0,1,1]
	ds_read_b128 v[40:43], v38 offset:16384
	v_pk_fma_f32 v[22:23], v[48:49], v[44:45], v[22:23] op_sel_hi:[0,1,1]
	v_pk_add_f32 v[22:23], v[22:23], v[24:25]
	v_mov_b32_e32 v49, v52
	v_pk_add_f32 v[22:23], v[28:29], v[22:23]
	s_waitcnt lgkmcnt(0)
	v_mov_b32_e32 v24, v41
	v_mov_b32_e32 v41, v43
	v_mov_b32_e32 v51, v34
	v_mov_b32_e32 v25, v42
	v_pk_mul_f32 v[28:29], v[48:49], v[40:41]
	v_mov_b32_e32 v44, v10
	v_pk_fma_f32 v[24:25], v[50:51], v[24:25], v[28:29]
	s_nop 0
	v_add_f32_e32 v24, v24, v25
	v_add_f32_e32 v39, v0, v24
	v_add_co_u32_e32 v24, vcc, s23, v20
	s_mov_b32 s23, 0xfff88000
	s_nop 0
	v_addc_co_u32_e32 v25, vcc, -1, v21, vcc
	v_add_co_u32_e32 v28, vcc, s23, v20
	s_mov_b32 s23, 0xfff94000
	s_nop 0
	v_addc_co_u32_e32 v29, vcc, -1, v21, vcc
	v_add_co_u32_e32 v40, vcc, s23, v20
	s_mov_b32 s23, 0xfffa0000
	s_nop 0
	v_addc_co_u32_e32 v41, vcc, -1, v21, vcc
	v_mov_b32_e32 v24, v124
	s_nop 0
	v_mov_b32_e32 v28, v125
	s_nop 0
	v_mov_b32_e32 v0, v126
	v_add_co_u32_e32 v40, vcc, s23, v20
	s_mov_b32 s23, 0xfffac000
	s_nop 0
	v_addc_co_u32_e32 v41, vcc, -1, v21, vcc
	v_mov_b32_e32 v34, v127
	ds_read_b128 v[40:43], v38 offset:2064
	s_waitcnt lgkmcnt(0)
	v_mov_b32_e32 v45, v40
	v_mov_b32_e32 v40, v11
	v_pk_mul_f32 v[10:11], v[28:29], v[40:41] op_sel_hi:[0,1]
	v_mov_b32_e32 v41, v42
	v_mov_b32_e32 v42, v13
	v_mov_b32_e32 v40, v12
	v_pk_fma_f32 v[10:11], v[24:25], v[44:45], v[10:11] op_sel_hi:[0,1,1]
	v_pk_mul_f32 v[12:13], v[34:35], v[42:43] op_sel_hi:[0,1]
	v_pk_fma_f32 v[12:13], v[0:1], v[40:41], v[12:13] op_sel_hi:[0,1,1]
	ds_read_b128 v[40:43], v38 offset:4112
	ds_read_b128 v[44:47], v38 offset:6160
	v_pk_add_f32 v[10:11], v[10:11], v[12:13]
	s_waitcnt lgkmcnt(1)
	v_mov_b32_e32 v12, v40
	s_waitcnt lgkmcnt(0)
	v_mov_b32_e32 v13, v44
	v_mov_b32_e32 v44, v41
	v_pk_add_f32 v[10:11], v[32:33], v[10:11]
	v_pk_mul_f32 v[32:33], v[28:29], v[44:45] op_sel_hi:[0,1]
	v_pk_fma_f32 v[12:13], v[24:25], v[12:13], v[32:33] op_sel_hi:[0,1,1]
	v_mov_b32_e32 v33, v46
	v_mov_b32_e32 v46, v43
	v_mov_b32_e32 v32, v42
	v_pk_mul_f32 v[40:41], v[34:35], v[46:47] op_sel_hi:[0,1]
	v_pk_fma_f32 v[32:33], v[0:1], v[32:33], v[40:41] op_sel_hi:[0,1,1]
	v_pk_add_f32 v[12:13], v[12:13], v[32:33]
	s_nop 0
	v_pk_add_f32 v[12:13], v[30:31], v[12:13]
	ds_read_b128 v[30:33], v38 offset:8208
	ds_read_b128 v[40:43], v38 offset:10256
	s_waitcnt lgkmcnt(1)
	v_mov_b32_e32 v44, v30
	s_waitcnt lgkmcnt(0)
	v_mov_b32_e32 v45, v40
	v_mov_b32_e32 v40, v31
	v_pk_mul_f32 v[30:31], v[28:29], v[40:41] op_sel_hi:[0,1]
	v_mov_b32_e32 v41, v42
	v_mov_b32_e32 v42, v33
	v_mov_b32_e32 v40, v32
	v_pk_mul_f32 v[32:33], v[34:35], v[42:43] op_sel_hi:[0,1]
	v_pk_fma_f32 v[30:31], v[24:25], v[44:45], v[30:31] op_sel_hi:[0,1,1]
	v_pk_fma_f32 v[32:33], v[0:1], v[40:41], v[32:33] op_sel_hi:[0,1,1]
	v_pk_add_f32 v[30:31], v[30:31], v[32:33]
	s_nop 0
	v_pk_add_f32 v[44:45], v[26:27], v[30:31]
	ds_read_b128 v[30:33], v38 offset:12304
	ds_read_b128 v[40:43], v38 offset:14352
	s_waitcnt lgkmcnt(1)
	v_mov_b32_e32 v26, v30
	s_waitcnt lgkmcnt(0)
	v_mov_b32_e32 v27, v40
	v_mov_b32_e32 v40, v31
	v_pk_mul_f32 v[30:31], v[28:29], v[40:41] op_sel_hi:[0,1]
	v_pk_fma_f32 v[26:27], v[24:25], v[26:27], v[30:31] op_sel_hi:[0,1,1]
	v_mov_b32_e32 v31, v42
	v_mov_b32_e32 v42, v33
	v_mov_b32_e32 v30, v32
	v_pk_mul_f32 v[32:33], v[34:35], v[42:43] op_sel_hi:[0,1]
	v_pk_fma_f32 v[30:31], v[0:1], v[30:31], v[32:33] op_sel_hi:[0,1,1]
	v_pk_add_f32 v[26:27], v[26:27], v[30:31]
	ds_read_b128 v[30:33], v38 offset:16400
	v_pk_add_f32 v[40:41], v[22:23], v[26:27]
	v_mov_b32_e32 v25, v34
	v_mov_b32_e32 v29, v0
	v_mov_b32_e32 v26, v6
	s_waitcnt lgkmcnt(0)
	v_mov_b32_e32 v22, v31
	v_mov_b32_e32 v31, v33
	v_mov_b32_e32 v23, v32
	v_pk_mul_f32 v[24:25], v[24:25], v[30:31]
	s_nop 0
	v_pk_fma_f32 v[22:23], v[28:29], v[22:23], v[24:25]
	s_nop 0
	v_add_f32_e32 v0, v22, v23
	v_add_co_u32_e32 v22, vcc, s23, v20
	s_mov_b32 s23, 0xfffb8000
	s_nop 0
	v_addc_co_u32_e32 v23, vcc, -1, v21, vcc
	v_mov_b32_e32 v28, v128
	v_add_co_u32_e32 v22, vcc, s23, v20
	s_mov_b32 s23, 0xfffc4000
	s_nop 0
	v_addc_co_u32_e32 v23, vcc, -1, v21, vcc
	v_mov_b32_e32 v30, v129
	v_add_co_u32_e32 v22, vcc, s23, v20
	s_mov_b32 s23, 0xfffd0000
	s_nop 0
	v_addc_co_u32_e32 v23, vcc, -1, v21, vcc
	v_add_f32_e32 v33, v39, v0
	v_mov_b32_e32 v0, v130
	v_add_co_u32_e32 v22, vcc, s23, v20
	s_mov_b32 s23, 0xfffdc000
	s_nop 0
	v_addc_co_u32_e32 v23, vcc, -1, v21, vcc
	v_mov_b32_e32 v32, v131
	ds_read_b128 v[22:25], v38 offset:2080
	s_waitcnt lgkmcnt(0)
	v_mov_b32_e32 v27, v22
	v_mov_b32_e32 v22, v7
	v_pk_mul_f32 v[6:7], v[30:31], v[22:23] op_sel_hi:[0,1]
	v_mov_b32_e32 v23, v24
	v_mov_b32_e32 v24, v9
	v_mov_b32_e32 v22, v8
	v_pk_fma_f32 v[6:7], v[28:29], v[26:27], v[6:7] op_sel_hi:[0,1,1]
	v_pk_mul_f32 v[8:9], v[32:33], v[24:25] op_sel_hi:[0,1]
	v_pk_fma_f32 v[8:9], v[0:1], v[22:23], v[8:9] op_sel_hi:[0,1,1]
	v_pk_add_f32 v[6:7], v[6:7], v[8:9]
	s_nop 0
	v_pk_add_f32 v[22:23], v[10:11], v[6:7]
	ds_read_b128 v[6:9], v38 offset:4128
	ds_read_b128 v[24:27], v38 offset:6176
	s_waitcnt lgkmcnt(1)
	v_mov_b32_e32 v10, v6
	s_waitcnt lgkmcnt(0)
	v_mov_b32_e32 v11, v24
	v_mov_b32_e32 v24, v7
	v_pk_mul_f32 v[6:7], v[30:31], v[24:25] op_sel_hi:[0,1]
	v_pk_fma_f32 v[6:7], v[28:29], v[10:11], v[6:7] op_sel_hi:[0,1,1]
	v_mov_b32_e32 v11, v26
	v_mov_b32_e32 v26, v9
	v_mov_b32_e32 v10, v8
	v_pk_mul_f32 v[8:9], v[32:33], v[26:27] op_sel_hi:[0,1]
	v_pk_fma_f32 v[8:9], v[0:1], v[10:11], v[8:9] op_sel_hi:[0,1,1]
	v_pk_add_f32 v[6:7], v[6:7], v[8:9]
	s_nop 0
	v_pk_add_f32 v[12:13], v[12:13], v[6:7]
	ds_read_b128 v[6:9], v38 offset:8224
	ds_read_b128 v[24:27], v38 offset:10272
	s_waitcnt lgkmcnt(1)
	v_mov_b32_e32 v10, v6
	s_waitcnt lgkmcnt(0)
	v_mov_b32_e32 v11, v24
	v_mov_b32_e32 v24, v7
	v_pk_mul_f32 v[6:7], v[30:31], v[24:25] op_sel_hi:[0,1]
	v_pk_fma_f32 v[6:7], v[28:29], v[10:11], v[6:7] op_sel_hi:[0,1,1]
	v_mov_b32_e32 v11, v26
	v_mov_b32_e32 v26, v9
	v_mov_b32_e32 v10, v8
	v_pk_mul_f32 v[8:9], v[32:33], v[26:27] op_sel_hi:[0,1]
	v_pk_fma_f32 v[8:9], v[0:1], v[10:11], v[8:9] op_sel_hi:[0,1,1]
	v_pk_add_f32 v[6:7], v[6:7], v[8:9]
	s_nop 0
	v_pk_add_f32 v[10:11], v[44:45], v[6:7]
	ds_read_b128 v[6:9], v38 offset:12320
	ds_read_b128 v[24:27], v38 offset:14368
	s_waitcnt lgkmcnt(1)
	v_mov_b32_e32 v42, v6
	s_waitcnt lgkmcnt(0)
	v_mov_b32_e32 v43, v24
	v_mov_b32_e32 v24, v7
	v_pk_mul_f32 v[6:7], v[30:31], v[24:25] op_sel_hi:[0,1]
	v_mov_b32_e32 v25, v26
	v_mov_b32_e32 v26, v9
	v_mov_b32_e32 v24, v8
	v_pk_mul_f32 v[8:9], v[32:33], v[26:27] op_sel_hi:[0,1]
	v_pk_fma_f32 v[8:9], v[0:1], v[24:25], v[8:9] op_sel_hi:[0,1,1]
	ds_read_b128 v[24:27], v38 offset:16416
	v_pk_fma_f32 v[6:7], v[28:29], v[42:43], v[6:7] op_sel_hi:[0,1,1]
	v_pk_add_f32 v[6:7], v[6:7], v[8:9]
	v_mov_b32_e32 v29, v32
	v_pk_add_f32 v[8:9], v[40:41], v[6:7]
	s_waitcnt lgkmcnt(0)
	v_mov_b32_e32 v6, v25
	v_mov_b32_e32 v25, v27
	v_mov_b32_e32 v31, v0
	v_mov_b32_e32 v7, v26
	v_pk_mul_f32 v[24:25], v[28:29], v[24:25]
	v_mov_b32_e32 v28, v2
	v_pk_fma_f32 v[6:7], v[30:31], v[6:7], v[24:25]
	s_nop 0
	v_add_f32_e32 v0, v6, v7
	v_add_co_u32_e32 v6, vcc, s23, v20
	s_mov_b32 s23, 0xfffe8000
	s_nop 0
	v_addc_co_u32_e32 v7, vcc, -1, v21, vcc
	v_add_co_u32_e32 v24, vcc, s23, v20
	s_mov_b32 s23, 0xffff4000
	s_nop 0
	v_addc_co_u32_e32 v25, vcc, -1, v21, vcc
	v_mov_b32_e32 v6, v132
	v_add_f32_e32 v33, v33, v0
	v_mov_b32_e32 v30, v133
	v_add_co_u32_e32 v24, vcc, s23, v20
	s_nop 1
	v_addc_co_u32_e32 v25, vcc, -1, v21, vcc
	v_mov_b32_e32 v0, v134
	v_mov_b32_e32 v32, v135
	ds_read_b128 v[24:27], v38 offset:2096
	v_lshl_add_u64 v[20:21], v[20:21], 0, s[26:27]
	s_waitcnt lgkmcnt(0)
	v_mov_b32_e32 v29, v24
	v_mov_b32_e32 v24, v3
	v_pk_mul_f32 v[2:3], v[30:31], v[24:25] op_sel_hi:[0,1]
	v_mov_b32_e32 v25, v26
	v_mov_b32_e32 v26, v5
	v_mov_b32_e32 v24, v4
	v_pk_fma_f32 v[2:3], v[6:7], v[28:29], v[2:3] op_sel_hi:[0,1,1]
	v_pk_mul_f32 v[4:5], v[32:33], v[26:27] op_sel_hi:[0,1]
	v_pk_fma_f32 v[4:5], v[0:1], v[24:25], v[4:5] op_sel_hi:[0,1,1]
	v_pk_add_f32 v[2:3], v[2:3], v[4:5]
	s_nop 0
	v_pk_add_f32 v[22:23], v[22:23], v[2:3]
	ds_read_b128 v[2:5], v38 offset:4144
	ds_read_b128 v[24:27], v38 offset:6192
	s_waitcnt lgkmcnt(1)
	v_mov_b32_e32 v28, v2
	s_waitcnt lgkmcnt(0)
	v_mov_b32_e32 v29, v24
	v_mov_b32_e32 v24, v3
	v_pk_mul_f32 v[2:3], v[30:31], v[24:25] op_sel_hi:[0,1]
	v_mov_b32_e32 v25, v26
	v_mov_b32_e32 v26, v5
	v_mov_b32_e32 v24, v4
	v_pk_mul_f32 v[4:5], v[32:33], v[26:27] op_sel_hi:[0,1]
	v_pk_fma_f32 v[2:3], v[6:7], v[28:29], v[2:3] op_sel_hi:[0,1,1]
	v_pk_fma_f32 v[4:5], v[0:1], v[24:25], v[4:5] op_sel_hi:[0,1,1]
	v_pk_add_f32 v[2:3], v[2:3], v[4:5]
	s_nop 0
	v_pk_add_f32 v[24:25], v[12:13], v[2:3]
	ds_read_b128 v[2:5], v38 offset:8240
	ds_read_b128 v[26:29], v38 offset:10288
	s_waitcnt lgkmcnt(1)
	v_mov_b32_e32 v12, v2
	s_waitcnt lgkmcnt(0)
	v_mov_b32_e32 v13, v26
	v_mov_b32_e32 v26, v3
	v_pk_mul_f32 v[2:3], v[30:31], v[26:27] op_sel_hi:[0,1]
	v_pk_fma_f32 v[2:3], v[6:7], v[12:13], v[2:3] op_sel_hi:[0,1,1]
	v_mov_b32_e32 v13, v28
	v_mov_b32_e32 v28, v5
	v_mov_b32_e32 v12, v4
	v_pk_mul_f32 v[4:5], v[32:33], v[28:29] op_sel_hi:[0,1]
	v_pk_fma_f32 v[4:5], v[0:1], v[12:13], v[4:5] op_sel_hi:[0,1,1]
	v_pk_add_f32 v[2:3], v[2:3], v[4:5]
	s_nop 0
	v_pk_add_f32 v[26:27], v[10:11], v[2:3]
	ds_read_b128 v[2:5], v38 offset:12336
	ds_read_b128 v[10:13], v38 offset:14384
	s_waitcnt lgkmcnt(1)
	v_mov_b32_e32 v28, v2
	s_waitcnt lgkmcnt(0)
	v_mov_b32_e32 v29, v10
	v_mov_b32_e32 v10, v3
	v_pk_mul_f32 v[2:3], v[30:31], v[10:11] op_sel_hi:[0,1]
	v_mov_b32_e32 v11, v12
	v_mov_b32_e32 v12, v5
	v_mov_b32_e32 v10, v4
	v_pk_mul_f32 v[4:5], v[32:33], v[12:13] op_sel_hi:[0,1]
	v_pk_fma_f32 v[2:3], v[6:7], v[28:29], v[2:3] op_sel_hi:[0,1,1]
	v_pk_fma_f32 v[4:5], v[0:1], v[10:11], v[4:5] op_sel_hi:[0,1,1]
	v_pk_add_f32 v[2:3], v[2:3], v[4:5]
	v_mov_b32_e32 v7, v32
	v_pk_add_f32 v[28:29], v[8:9], v[2:3]
	ds_read_b128 v[2:5], v38 offset:16432
	v_mov_b32_e32 v31, v0
	v_add_u32_e32 v38, 64, v38
	s_waitcnt lgkmcnt(0)
	v_mov_b32_e32 v8, v3
	v_mov_b32_e32 v3, v5
	v_mov_b32_e32 v9, v4
	v_pk_mul_f32 v[2:3], v[6:7], v[2:3]
	s_nop 0
	v_pk_fma_f32 v[2:3], v[30:31], v[8:9], v[2:3]
	s_nop 0
	v_add_f32_e32 v0, v2, v3
	v_add_f32_e32 v0, v33, v0
	s_cbranch_scc0 .LBB0_1022
	v_add_u32_e32 v2, 0xa000, v37
	ds_write2_b32 v2, v22, v23 offset1:32
	ds_write2_b32 v2, v24, v25 offset0:64 offset1:96
	ds_write2_b32 v2, v26, v27 offset0:128 offset1:160
	ds_write2_b32 v2, v28, v29 offset0:192 offset1:224
	ds_write_b32 v37, v0 offset:41984
	s_waitcnt lgkmcnt(0)
	s_barrier
	s_and_saveexec_b64 s[22:23], s[38:39]
	s_cbranch_execz .LBB0_1020
	s_mul_i32 s25, s24, 0x1800
	s_add_i32 s26, s25, s0
	v_or_b32_e32 v2, s26, v14
	v_readlane_b32 s56, v253, 6
	v_ashrrev_i32_e32 v3, 31, v2
	v_readlane_b32 s58, v253, 8
	v_readlane_b32 s59, v253, 9
	v_readlane_b32 s64, v253, 14
	v_readlane_b32 s65, v253, 15
	s_mul_hi_i32 s25, s24, 9
	s_mul_i32 s24, s24, 9
	v_readlane_b32 s64, v253, 49
	v_lshl_add_u64 v[2:3], v[2:3], 2, s[58:59]
	v_lshl_add_u64 v[4:5], s[0:1], 2, v[16:17]
	s_mov_b64 s[0:1], 0
	v_mov_b32_e32 v0, v184
	v_readlane_b32 s57, v253, 7
	v_readlane_b32 s60, v253, 10
	v_readlane_b32 s61, v253, 11
	v_readlane_b32 s62, v253, 12
	v_readlane_b32 s63, v253, 13
	v_readlane_b32 s66, v253, 16
	v_readlane_b32 s67, v253, 17
	v_readlane_b32 s68, v253, 18
	v_readlane_b32 s69, v253, 19
	v_readlane_b32 s70, v253, 20
	v_readlane_b32 s71, v253, 21
	v_readlane_b32 s65, v253, 50
